# phases 8 and 18 CU-partner offset raised to 17 us
# baseline (speedup 1.0000x reference)
.LBB0_491:
	s_getreg_b32 s98, hwreg(HW_REG_HW_ID, 0, 4)
	s_cmp_eq_u32 s98, 0
	s_cbranch_scc1 .Lstg0_done
	s_memrealtime s[98:99]
	s_waitcnt lgkmcnt(0)
	s_add_u32 s98, s98, 1700
